# ssm_prep km inner loop rewritten with scalar FMAs; attention row-max via permlane16/32 swap instead of two ds_bpermute; on top of v006
# speedup vs baseline: 1.0047x; 1.0025x over previous
; __device__ void ssm_prep(const Params& p, int g, int part, float* L) {
;     ...
;   for (int i = tid; i < 4096; i += 512) { const int d = i >> 8, hp = (i >> 4) & 15, h = i & 15; float s = 0.f;
;     for (int pp = 0; pp < 64; ++pp) { const float c_r = cr[hp * 64 + pp], c_i = ci[hp * 64 + pp], pr = powr[d * 64 + pp], pi = powi[d * 64 + pp];
;       const float wr_ = c_r * pr - c_i * pi, wi_ = c_r * pi + c_i * pr; s += wr_ * bbr[pp * 16 + h] - wi_ * bbi[pp * 16 + h]; }
;     if (d == 0 && hp == h) s += p.in[22][g * 16 + h];
;     km[i] = s; }
.LBB0_21:
	v_add_u32_e32 v32, s10, v17
	v_add_u32_e32 v40, s10, v26
	v_add_u32_e32 v50, 0x1000, v27
	ds_read2_b32 v[44:45], v27 offset1:16
	ds_read2_b32 v[46:47], v27 offset0:32 offset1:48
	ds_read_b128 v[28:31], v32
	ds_read_b128 v[32:35], v32 offset:4096
	ds_read_b128 v[36:39], v40
	ds_read_b128 v[40:43], v40 offset:4352
	ds_read2_b32 v[48:49], v50 offset1:16
	ds_read2_b32 v[50:51], v50 offset0:32 offset1:48
	s_add_i32 s10, s10, 16
	v_add_u32_e32 v27, 0x100, v27
	s_waitcnt lgkmcnt(0)
	v_mul_f32_e32 v52, v28, v36
	v_mul_f32_e32 v53, v28, v40
	v_fma_f32 v52, -v32, v40, v52
	v_fmac_f32_e32 v53, v32, v36
	v_mul_f32_e32 v54, v29, v37
	v_mul_f32_e32 v55, v29, v41
	v_fma_f32 v54, -v33, v41, v54
	v_fmac_f32_e32 v55, v33, v37
	v_mul_f32_e32 v56, v30, v38
	v_mul_f32_e32 v57, v30, v42
	v_fma_f32 v56, -v34, v42, v56
	v_fmac_f32_e32 v57, v34, v38
	v_mul_f32_e32 v58, v31, v39
	v_mul_f32_e32 v59, v31, v43
	v_fma_f32 v58, -v35, v43, v58
	v_fmac_f32_e32 v59, v35, v39
	v_fmac_f32_e32 v7, v52, v44
	v_fma_f32 v7, -v53, v48, v7
	v_fmac_f32_e32 v7, v54, v45
	v_fma_f32 v7, -v55, v49, v7
	v_fmac_f32_e32 v7, v56, v46
	v_fma_f32 v7, -v57, v50, v7
	v_fmac_f32_e32 v7, v58, v47
	v_fma_f32 v7, -v59, v51, v7
	s_cmpk_eq_i32 s10, 0x100
	s_cbranch_scc0 .LBB0_21
	v_cmp_gt_u32_e32 vcc, s2, v6
	s_and_b64 s[12:13], s[6:7], vcc
	s_and_saveexec_b64 s[10:11], s[12:13]
	s_cbranch_execz .LBB0_19
	global_load_dword v26, v[4:5], off
	s_waitcnt vmcnt(0)
	v_add_f32_e32 v7, v7, v26
	s_branch .LBB0_19

; __device__ __forceinline__ unsigned cvt_pk_bf16(float lo, float hi) { unsigned r; asm("v_cvt_pk_bf16_f32 %0, %1, %2" : "=v"(r) : "v"(lo), "v"(hi)); return r; }
; #define LAS __attribute__((address_space(3)))
; #define MFMA16(a, b, c) __builtin_amdgcn_mfma_f32_16x16x32_bf16((a), (b), (c), 0, 0, 0)
; #define ATT_STORE(buf_) do { _Pragma("unroll") for (int i = 0; i < 8; ++i) \
;     *(LAS u32x4*)(st0 + (buf_) * ATT_BUF + ((i >> 2) * 2 + ((i >> 1) & 1)) * ATT_TILE + (i & 1) * 32 * 272) = t[i]; } while (0)
; __device__ __forceinline__ void attn_wg_item(const Params& p, int item, LAS unsigned char* lds) {
;     ...
;     tmax = fmaxf(tmax, __shfl_xor(tmax, 16)); tmax = fmaxf(tmax, __shfl_xor(tmax, 32));
;     const float mnew = fmaxf(mrun, tmax), alpha = __builtin_amdgcn_exp2f(mrun - mnew); mrun = mnew;
;     float psum = 0.f;
; #pragma unroll
;     for (int kt = 0; kt < 4; ++kt)
; #pragma unroll
;       for (int i = 0; i < 4; ++i) { const float e = __builtin_amdgcn_exp2f(S[kt][i] - mnew); S[kt][i] = e; psum += e; }
;     lsum = lsum * alpha + psum;
; #pragma unroll
;     for (int dt = 0; dt < 8; ++dt) O[dt] *= alpha;
;     bf16x8 Pf[2];
; #pragma unroll
;     for (int s2 = 0; s2 < 2; ++s2) { u32x4 wv; wv.x = cvt_pk_bf16(S[2 * s2][0], S[2 * s2][1]); wv.y = cvt_pk_bf16(S[2 * s2][2], S[2 * s2][3]);
;       wv.z = cvt_pk_bf16(S[2 * s2 + 1][0], S[2 * s2 + 1][1]); wv.w = cvt_pk_bf16(S[2 * s2 + 1][2], S[2 * s2 + 1][3]); Pf[s2] = __builtin_bit_cast(bf16x8, wv); }
;     { const int qq = l15 >> 2, pp = l15 & 3; LAS unsigned char* vb = Vl + (4 * kq + qq) * 272 + pp * 8;
; #pragma unroll
;       for (int s2 = 0; s2 < 2; ++s2)
; #pragma unroll
;         for (int dt = 0; dt < 8; ++dt) {
;           const s16x4 lo = __builtin_amdgcn_ds_read_tr16_b64_v4i16((LAS s16x4*)(vb + (32 * s2) * 272 + dt * 32));
;           const s16x4 hi = __builtin_amdgcn_ds_read_tr16_b64_v4i16((LAS s16x4*)(vb + (32 * s2 + 16) * 272 + dt * 32));
;           const bf16x8 Vf = __builtin_shufflevector(lo, hi, 0, 1, 2, 3, 4, 5, 6, 7);
;           O[dt] = MFMA16(Vf, Pf[s2], O[dt]); } }
;     if (ps < 8) ATT_STORE((ps + 1) & 1);
.LBB0_822:
	s_or_b64 exec, exec, s[14:15]
	s_waitcnt lgkmcnt(0)
	s_nop 0
	v_add_f32_e32 v136, v83, v136
	v_max_f32_e32 v80, v158, v158
	v_max_f32_e32 v80, v80, v136
	s_andn2_b64 vcc, exec, s[10:11]
	v_mov_b32_e32 v81, v80
	v_mov_b32_e32 v166, v80
	s_nop 1
	v_permlane16_swap_b32_e32 v81, v166
	v_max_f32_e32 v80, v81, v166
	v_mov_b32_e32 v81, v80
	v_mov_b32_e32 v166, v80
	s_nop 1
	v_permlane32_swap_b32_e32 v81, v166
	v_max3_f32 v81, v155, v81, v166
	v_sub_f32_e32 v80, v155, v81
	v_sub_f32_e32 v83, v123, v81
	v_sub_f32_e32 v123, v136, v81
	v_add3_u32 v136, s16, v139, v140
	v_exp_f32_e32 v80, v80
	v_sub_f32_e32 v88, v128, v81
	v_sub_f32_e32 v89, v129, v81
	v_sub_f32_e32 v90, v130, v81
	v_sub_f32_e32 v91, v131, v81
	v_sub_f32_e32 v92, v132, v81
	v_sub_f32_e32 v93, v133, v81
	v_sub_f32_e32 v94, v134, v81
	v_sub_f32_e32 v95, v135, v81
	ds_read_b64_tr_b16 v[184:185], v136 offset:34816
	ds_read_b64_tr_b16 v[186:187], v136 offset:39168
	ds_read_b64_tr_b16 v[188:189], v136 offset:34848
	ds_read_b64_tr_b16 v[190:191], v136 offset:39200
	ds_read_b64_tr_b16 v[192:193], v136 offset:34880
	ds_read_b64_tr_b16 v[194:195], v136 offset:39232
	ds_read_b64_tr_b16 v[196:197], v136 offset:34912
	ds_read_b64_tr_b16 v[198:199], v136 offset:39264
	ds_read_b64_tr_b16 v[200:201], v136 offset:34944
	ds_read_b64_tr_b16 v[202:203], v136 offset:39296
	ds_read_b64_tr_b16 v[204:205], v136 offset:34976
	ds_read_b64_tr_b16 v[206:207], v136 offset:39328
	ds_read_b64_tr_b16 v[208:209], v136 offset:35008
	ds_read_b64_tr_b16 v[210:211], v136 offset:39360
	v_sub_f32_e32 v82, v122, v81
	v_sub_f32_e32 v84, v124, v81
	v_sub_f32_e32 v85, v125, v81
	v_sub_f32_e32 v86, v126, v81
	v_sub_f32_e32 v87, v127, v81
	v_pk_mul_f32 v[78:79], v[78:79], v[80:81] op_sel_hi:[1,0]
	v_pk_mul_f32 v[76:77], v[76:77], v[80:81] op_sel_hi:[1,0]
	v_pk_mul_f32 v[74:75], v[74:75], v[80:81] op_sel_hi:[1,0]
	v_pk_mul_f32 v[72:73], v[72:73], v[80:81] op_sel_hi:[1,0]
	v_pk_mul_f32 v[70:71], v[70:71], v[80:81] op_sel_hi:[1,0]
	v_pk_mul_f32 v[68:69], v[68:69], v[80:81] op_sel_hi:[1,0]
	v_pk_mul_f32 v[66:67], v[66:67], v[80:81] op_sel_hi:[1,0]
	v_pk_mul_f32 v[64:65], v[64:65], v[80:81] op_sel_hi:[1,0]
	v_exp_f32_e32 v82, v82
	v_exp_f32_e32 v83, v83
	v_exp_f32_e32 v84, v84
	v_exp_f32_e32 v85, v85
	v_exp_f32_e32 v86, v86
	v_exp_f32_e32 v87, v87
	v_exp_f32_e32 v88, v88
	v_exp_f32_e32 v89, v89
	v_cvt_pk_bf16_f32 v124, v82, v83
	v_cvt_pk_bf16_f32 v125, v84, v85
	v_cvt_pk_bf16_f32 v126, v86, v87
	v_cvt_pk_bf16_f32 v127, v88, v89
	v_pk_mul_f32 v[62:63], v[62:63], v[80:81] op_sel_hi:[1,0]
	s_waitcnt lgkmcnt(12)
	v_mfma_f32_16x16x32_bf16 v[76:79], v[184:187], v[124:127], v[76:79]
	ds_read_b64_tr_b16 v[212:213], v136 offset:35040
	ds_read_b64_tr_b16 v[214:215], v136 offset:39392
	v_pk_mul_f32 v[60:61], v[60:61], v[80:81] op_sel_hi:[1,0]
	v_pk_mul_f32 v[58:59], v[58:59], v[80:81] op_sel_hi:[1,0]
	s_waitcnt lgkmcnt(12)
	v_mfma_f32_16x16x32_bf16 v[72:75], v[188:191], v[124:127], v[72:75]
	ds_read_b64_tr_b16 v[216:217], v136 offset:43520
	ds_read_b64_tr_b16 v[218:219], v136 offset:47872
	v_mul_f32_e64 v56, v56, v80
	v_mul_f32_e64 v57, v57, v80
	v_pk_mul_f32 v[38:39], v[38:39], v[80:81] op_sel_hi:[1,0]
	v_pk_mul_f32 v[36:37], v[36:37], v[80:81] op_sel_hi:[1,0]
	s_waitcnt lgkmcnt(12)
	v_mfma_f32_16x16x32_bf16 v[68:71], v[192:195], v[124:127], v[68:71]
	ds_read_b64_tr_b16 v[220:221], v136 offset:43552
	ds_read_b64_tr_b16 v[222:223], v136 offset:47904
	v_mul_f32_e64 v30, v30, v80
	v_mul_f32_e64 v31, v31, v80
	v_pk_mul_f32 v[28:29], v[28:29], v[80:81] op_sel_hi:[1,0]
	v_sub_f32_e32 v122, v157, v81
	s_waitcnt lgkmcnt(12)
	v_mfma_f32_16x16x32_bf16 v[64:67], v[196:199], v[124:127], v[64:67]
	ds_read_b64_tr_b16 v[224:225], v136 offset:43584
	ds_read_b64_tr_b16 v[226:227], v136 offset:47936
	v_exp_f32_e32 v90, v90
	v_exp_f32_e32 v91, v91
	s_waitcnt lgkmcnt(12)
	v_mfma_f32_16x16x32_bf16 v[60:63], v[200:203], v[124:127], v[60:63]
	ds_read_b64_tr_b16 v[228:229], v136 offset:43616
	ds_read_b64_tr_b16 v[230:231], v136 offset:47968
	v_exp_f32_e32 v92, v92
	v_exp_f32_e32 v93, v93
	v_exp_f32_e32 v94, v94
	s_waitcnt lgkmcnt(12)
	v_mfma_f32_16x16x32_bf16 v[56:59], v[204:207], v[124:127], v[56:59]
	ds_read_b64_tr_b16 v[232:233], v136 offset:43648
	ds_read_b64_tr_b16 v[234:235], v136 offset:48000
	v_exp_f32_e32 v95, v95
	v_exp_f32_e32 v122, v122
	s_waitcnt lgkmcnt(12)
	v_mfma_f32_16x16x32_bf16 v[36:39], v[208:211], v[124:127], v[36:39]
	ds_read_b64_tr_b16 v[236:237], v136 offset:43680
	ds_read_b64_tr_b16 v[238:239], v136 offset:48032
	v_exp_f32_e32 v123, v123
	v_cvt_pk_bf16_f32 v128, v90, v91
	v_cvt_pk_bf16_f32 v129, v92, v93
	s_waitcnt lgkmcnt(12)
	v_mfma_f32_16x16x32_bf16 v[28:31], v[212:215], v[124:127], v[28:31]
	ds_read_b64_tr_b16 v[240:241], v136 offset:43712
	ds_read_b64_tr_b16 v[242:243], v136 offset:48064
	v_cvt_pk_bf16_f32 v130, v94, v95
	v_cvt_pk_bf16_f32 v131, v122, v123
	s_nop 1
	s_waitcnt lgkmcnt(12)
	v_mfma_f32_16x16x32_bf16 v[76:79], v[216:219], v[128:131], v[76:79]
	ds_read_b64_tr_b16 v[172:173], v136 offset:43744
	ds_read_b64_tr_b16 v[174:175], v136 offset:48096
	s_waitcnt lgkmcnt(12)
	v_mfma_f32_16x16x32_bf16 v[72:75], v[220:223], v[128:131], v[72:75]
	s_waitcnt lgkmcnt(10)
	v_mfma_f32_16x16x32_bf16 v[68:71], v[224:227], v[128:131], v[68:71]
	s_waitcnt lgkmcnt(8)
	v_mfma_f32_16x16x32_bf16 v[64:67], v[228:231], v[128:131], v[64:67]
	s_waitcnt lgkmcnt(6)
	v_mfma_f32_16x16x32_bf16 v[60:63], v[232:235], v[128:131], v[60:63]
	s_waitcnt lgkmcnt(4)
	v_mfma_f32_16x16x32_bf16 v[56:59], v[236:239], v[128:131], v[56:59]
	s_waitcnt lgkmcnt(2)
	v_mfma_f32_16x16x32_bf16 v[36:39], v[240:243], v[128:131], v[36:39]
	s_waitcnt lgkmcnt(0)
	v_mfma_f32_16x16x32_bf16 v[28:31], v[172:175], v[128:131], v[28:31]
	s_cbranch_vccnz .LBB0_824
	s_andn2_b32 s10, 1, s8
	s_mul_i32 s10, s10, 0x11000
	v_add_u32_e32 v124, s10, v137
	s_waitcnt vmcnt(0)
	ds_write_b128 v124, v[0:3]
	ds_write_b128 v124, v[8:11] offset:8704
	ds_write_b128 v124, v[4:7] offset:17408
	ds_write_b128 v124, v[16:19] offset:26112
	ds_write_b128 v124, v[12:15] offset:34816
	ds_write_b128 v124, v[24:27] offset:43520
	ds_write_b128 v124, v[20:23] offset:52224
	ds_write_b128 v124, v[32:35] offset:60928
